# as v42 plus strategy 7.12 (shorten the serial row-max to branch chain between S and PV MFMAs): redundant self-max canonicalisations after the permlane deleted in MLA loop, MLA first tile and SWA loop;
# speedup vs baseline: 1.0062x; 1.0062x over previous
; #define LAS __attribute__((address_space(3)))
; __device__ __forceinline__ int crow(int r, int hi) { return (r & 3) + 8 * (r >> 2) + 4 * hi; }
; template <int MODE> __device__ __forceinline__ void attn_unit(const Unit& a, char* shm) {
;     ...
;         if (MODE == 1) active = (64 * t + 63 >= tq0 - 128) && (64 * t <= tq0 + 31 + 128);
;         if (active) {
;             const lds_cptr kp = shm3 + LDS_K + s * KSLOT + hi * 1024 + r32 * 16;
;             f32x16 p0 = negm, p1 = negm;
; #pragma unroll
;             for (int d0 = 0; d0 < ND; ++d0) {
;                 const bf16x8 b0 = *(const LAS bf16x8*)(kp + d0 * 2048), b1 = *(const LAS bf16x8*)(kp + d0 * 2048 + 512);
;                 p0 = __builtin_amdgcn_mfma_f32_32x32x16_bf16(b0, qr[d0], p0, 0, 0, 0);
;                 p1 = __builtin_amdgcn_mfma_f32_32x32x16_bf16(b1, qr[d0], p1, 0, 0, 0);
;             }
;             if (MODE == 1) {
; #pragma unroll
;                 for (int r = 0; r < 16; ++r) { const int ks = 64 * t + crow(r, hi); const int r0 = abs(tq - ks), r1 = abs(tq - ks - 32);
;                     p0[r] = (r0 <= 128) ? p0[r] - a.slope2 * (float)r0 : -INFINITY; p1[r] = (r1 <= 128) ? p1[r] - a.slope2 * (float)r1 : -INFINITY; }
.LBB0_1328:
	s_add_i32 s0, s41, 63
	s_cmp_ge_i32 s0, s31
	s_cselect_b64 s[0:1], -1, 0
	s_cmp_le_i32 s41, s40
	s_cselect_b64 s[46:47], -1, 0
	s_and_b64 s[0:1], s[0:1], s[46:47]
	s_andn2_b64 vcc, exec, s[0:1]
	s_cbranch_vccnz .LBB0_1336
	s_mulk_i32 s34, 0x3000
	v_add_u32_e32 v134, s34, v166
	ds_read_b128 v[64:67], v134
	ds_read_b128 v[142:145], v134 offset:512
	v_add_u32_e32 v131, v168, v117
	v_add_u32_e32 v130, v168, v116
	v_sub_u32_e32 v135, 0, v131
	s_waitcnt lgkmcnt(1)
	v_mfma_f32_32x32x16_bf16 v[48:63], v[64:67], v[82:85], v[32:47]
	v_mov_b64_e32 v[78:79], v[46:47]
	v_mov_b64_e32 v[76:77], v[44:45]
	v_mov_b64_e32 v[74:75], v[42:43]
	v_mov_b64_e32 v[72:73], v[40:41]
	v_mov_b64_e32 v[70:71], v[38:39]
	v_mov_b64_e32 v[68:69], v[36:37]
	v_mov_b64_e32 v[66:67], v[34:35]
	v_mov_b64_e32 v[64:65], v[32:33]
	v_max_i32_e32 v135, v131, v135
	v_sub_u32_e32 v131, 0, v130
	s_waitcnt lgkmcnt(0)
	v_mfma_f32_32x32x16_bf16 v[64:79], v[142:145], v[82:85], v[64:79]
	ds_read_b128 v[142:145], v134 offset:2048
	ds_read_b128 v[146:149], v134 offset:2560
	v_max_i32_e32 v154, v130, v131
	v_cvt_f32_u32_e32 v131, v135
	v_cvt_f32_u32_e32 v130, v154
	v_cmp_gt_u32_e32 vcc, s13, v135
	s_waitcnt lgkmcnt(0)
	v_mfma_f32_32x32x16_bf16 v[64:79], v[146:149], v[86:89], v[64:79]
	v_mfma_f32_32x32x16_bf16 v[48:63], v[142:145], v[86:89], v[48:63]
	ds_read_b128 v[142:145], v134 offset:4608
	ds_read_b128 v[146:149], v134 offset:4096
	ds_read_b128 v[150:153], v134 offset:6656
	s_waitcnt lgkmcnt(2)
	v_mfma_f32_32x32x16_bf16 v[64:79], v[142:145], v[90:93], v[64:79]
	ds_read_b128 v[142:145], v134 offset:6144
	v_add_u32_e32 v134, v168, v100
	s_waitcnt lgkmcnt(1)
	v_mfma_f32_32x32x16_bf16 v[64:79], v[150:153], v[94:97], v[64:79]
	v_add_u32_e32 v150, v168, v101
	v_mfma_f32_32x32x16_bf16 v[48:63], v[146:149], v[90:93], v[48:63]
	s_nop 9
	v_fma_f32 v130, -v98, v130, v64
	v_fma_f32 v131, -v99, v131, v65
	v_cndmask_b32_e32 v64, v180, v131, vcc
	v_cmp_gt_u32_e32 vcc, s13, v154
	s_nop 1
	v_cndmask_b32_e32 v65, v180, v130, vcc
	s_waitcnt lgkmcnt(0)
	v_mfma_f32_32x32x16_bf16 v[48:63], v[142:145], v[94:97], v[48:63]
	v_sub_u32_e32 v130, 0, v150
	v_max_i32_e32 v135, v150, v130
	v_sub_u32_e32 v130, 0, v134
	v_max_i32_e32 v146, v134, v130
	v_cvt_f32_u32_e32 v131, v135
	v_cvt_f32_u32_e32 v130, v146
	v_cmp_gt_u32_e32 vcc, s13, v135
	v_add_u32_e32 v145, v103, v168
	v_add_u32_e32 v144, v102, v168
	s_nop 2
	v_pk_fma_f32 v[130:131], v[98:99], v[130:131], v[48:49] neg_lo:[1,0,0] neg_hi:[1,0,0]
	v_add_u32_e32 v49, v168, v118
	v_cndmask_b32_e32 v48, v180, v131, vcc
	v_add_u32_e32 v131, v168, v119
	v_sub_u32_e32 v134, 0, v131
	v_max_i32_e32 v142, v131, v134
	v_sub_u32_e32 v131, 0, v49
	v_max_i32_e32 v143, v49, v131
	v_cvt_f32_u32_e32 v135, v142
	v_cvt_f32_u32_e32 v134, v143
	v_cmp_gt_u32_e32 vcc, s13, v146
	s_nop 1
	v_cndmask_b32_e32 v49, v180, v130, vcc
	v_pk_fma_f32 v[130:131], v[98:99], v[134:135], v[66:67] neg_lo:[1,0,0] neg_hi:[1,0,0]
	v_sub_u32_e32 v66, 0, v145
	v_max_i32_e32 v145, v145, v66
	v_sub_u32_e32 v66, 0, v144
	v_max_i32_e32 v144, v144, v66
	v_cvt_f32_u32_e32 v135, v145
	v_cvt_f32_u32_e32 v134, v144
	v_cmp_gt_u32_e32 vcc, s13, v142
	s_nop 1
	v_cndmask_b32_e32 v66, v180, v131, vcc
	v_cmp_gt_u32_e32 vcc, s13, v143
	s_nop 1
	v_cndmask_b32_e32 v67, v180, v130, vcc
	v_pk_fma_f32 v[130:131], v[98:99], v[134:135], v[50:51] neg_lo:[1,0,0] neg_hi:[1,0,0]
	v_cmp_gt_u32_e32 vcc, s13, v145
	v_add_u32_e32 v51, v168, v120
	v_add_u32_e32 v145, v105, v168
	v_cndmask_b32_e32 v50, v180, v131, vcc
	v_add_u32_e32 v131, v168, v121
	v_sub_u32_e32 v134, 0, v131
	v_max_i32_e32 v142, v131, v134
	v_sub_u32_e32 v131, 0, v51
	v_max_i32_e32 v143, v51, v131
	v_cvt_f32_u32_e32 v135, v142
	v_cvt_f32_u32_e32 v134, v143
	v_cmp_gt_u32_e32 vcc, s13, v144
	v_add_u32_e32 v144, v104, v168
	s_nop 0
	v_cndmask_b32_e32 v51, v180, v130, vcc
	v_pk_fma_f32 v[130:131], v[98:99], v[134:135], v[68:69] neg_lo:[1,0,0] neg_hi:[1,0,0]
	v_sub_u32_e32 v68, 0, v145
	v_max_i32_e32 v145, v145, v68
	v_sub_u32_e32 v68, 0, v144
	v_max_i32_e32 v144, v144, v68
	v_cvt_f32_u32_e32 v135, v145
	v_cvt_f32_u32_e32 v134, v144
	v_cmp_gt_u32_e32 vcc, s13, v142
	s_nop 1
	v_cndmask_b32_e32 v68, v180, v131, vcc
	v_cmp_gt_u32_e32 vcc, s13, v143
	s_nop 1
	v_cndmask_b32_e32 v69, v180, v130, vcc
	v_pk_fma_f32 v[130:131], v[98:99], v[134:135], v[52:53] neg_lo:[1,0,0] neg_hi:[1,0,0]
	v_cmp_gt_u32_e32 vcc, s13, v145
	v_add_u32_e32 v53, v168, v122
	v_add_u32_e32 v145, v107, v168
	v_cndmask_b32_e32 v52, v180, v131, vcc
	v_add_u32_e32 v131, v168, v123
	v_sub_u32_e32 v134, 0, v131
	v_max_i32_e32 v142, v131, v134
	v_sub_u32_e32 v131, 0, v53
	v_max_i32_e32 v143, v53, v131
	v_cvt_f32_u32_e32 v135, v142
	v_cvt_f32_u32_e32 v134, v143
	v_cmp_gt_u32_e32 vcc, s13, v144
	v_add_u32_e32 v144, v106, v168
	s_nop 0
	v_cndmask_b32_e32 v53, v180, v130, vcc
	v_pk_fma_f32 v[130:131], v[98:99], v[134:135], v[70:71] neg_lo:[1,0,0] neg_hi:[1,0,0]
	v_sub_u32_e32 v70, 0, v145
	v_max_i32_e32 v145, v145, v70
	v_sub_u32_e32 v70, 0, v144
	v_max_i32_e32 v144, v144, v70
	v_cvt_f32_u32_e32 v135, v145
	v_cvt_f32_u32_e32 v134, v144
	v_cmp_gt_u32_e32 vcc, s13, v142
	s_nop 1
	v_cndmask_b32_e32 v70, v180, v131, vcc
	v_cmp_gt_u32_e32 vcc, s13, v143
	s_nop 1
	v_cndmask_b32_e32 v71, v180, v130, vcc
	v_pk_fma_f32 v[130:131], v[98:99], v[134:135], v[54:55] neg_lo:[1,0,0] neg_hi:[1,0,0]
	v_cmp_gt_u32_e32 vcc, s13, v145
	v_add_u32_e32 v55, v168, v124
	v_add_u32_e32 v145, v109, v168
	v_cndmask_b32_e32 v54, v180, v131, vcc
	v_add_u32_e32 v131, v168, v125
	v_sub_u32_e32 v134, 0, v131
	v_max_i32_e32 v142, v131, v134
	v_sub_u32_e32 v131, 0, v55
	v_max_i32_e32 v143, v55, v131
	v_cvt_f32_u32_e32 v135, v142
; __device__ __forceinline__ int crow(int r, int hi) { return (r & 3) + 8 * (r >> 2) + 4 * hi; }
; __device__ __forceinline__ float halfmax(float m) { auto rr = __builtin_amdgcn_permlane32_swap(__float_as_uint(m), __float_as_uint(m), false, false); return fmaxf(__uint_as_float(rr[0]), __uint_as_float(rr[1])); }
; #define MX3(a_, b_, c_) __builtin_fmaxf(__builtin_fmaxf((a_), (b_)), (c_))
; template <int MODE> __device__ __forceinline__ void attn_unit(const Unit& a, char* shm) {
;     ...
;                 for (int r = 0; r < 16; ++r) { const int ks = 64 * t + crow(r, hi); const int r0 = abs(tq - ks), r1 = abs(tq - ks - 32);
;                     p0[r] = (r0 <= 128) ? p0[r] - a.slope2 * (float)r0 : -INFINITY; p1[r] = (r1 <= 128) ? p1[r] - a.slope2 * (float)r1 : -INFINITY; }
;             }
;     ...
;             float ra = MX3(p0[0], p0[1], p1[0]), rb = MX3(p0[2], p0[3], p1[1]); ra = MX3(ra, p1[2], p1[3]);
; #pragma unroll
;             for (int r = 4; r < 16; r += 4) { ra = MX3(ra, p0[r], p0[r + 1]); rb = MX3(rb, p0[r + 2], p0[r + 3]); ra = MX3(ra, p1[r], p1[r + 1]); rb = MX3(rb, p1[r + 2], p1[r + 3]); }
;     ...
;             float rm = halfmax(__builtin_fmaxf(ra, rb));
;             const bool first = (MODE == 0) && (t == a.t_lo);
;             if (first || __any(rm > THR)) {
;                 const float dl = first ? rm : fmaxf(rm, 0.f);
;                 mhat += dl;
; #pragma unroll
;                 for (int r = 0; r < 16; ++r) { p0[r] -= dl; p1[r] -= dl; negm[r] = -mhat; }
;                 if (!first) {
;                     const float f = __builtin_amdgcn_exp2f(-dl); l_reg *= f;
;                     if (hi == 0) wsf[r32] = f;
; #pragma unroll
;                     for (int r = 0; r < 16; ++r) { const float fr_ = wsf[crow(r, hi)]; o[0][r] *= fr_; o[1][r] *= fr_; }
	v_cvt_f32_u32_e32 v134, v143
	v_cmp_gt_u32_e32 vcc, s13, v144
	v_add_u32_e32 v144, v108, v168
	s_nop 0
	v_cndmask_b32_e32 v55, v180, v130, vcc
	v_pk_fma_f32 v[130:131], v[98:99], v[134:135], v[72:73] neg_lo:[1,0,0] neg_hi:[1,0,0]
	v_sub_u32_e32 v72, 0, v145
	v_max_i32_e32 v145, v145, v72
	v_sub_u32_e32 v72, 0, v144
	v_max_i32_e32 v144, v144, v72
	v_cvt_f32_u32_e32 v135, v145
	v_cvt_f32_u32_e32 v134, v144
	v_cmp_gt_u32_e32 vcc, s13, v142
	s_nop 1
	v_cndmask_b32_e32 v72, v180, v131, vcc
	v_cmp_gt_u32_e32 vcc, s13, v143
	s_nop 1
	v_cndmask_b32_e32 v73, v180, v130, vcc
	v_pk_fma_f32 v[130:131], v[98:99], v[134:135], v[56:57] neg_lo:[1,0,0] neg_hi:[1,0,0]
	v_cmp_gt_u32_e32 vcc, s13, v145
	v_add_u32_e32 v57, v168, v126
	s_nop 0
	v_cndmask_b32_e32 v56, v180, v131, vcc
	v_add_u32_e32 v131, v168, v127
	v_sub_u32_e32 v134, 0, v131
	v_max_i32_e32 v142, v131, v134
	v_sub_u32_e32 v131, 0, v57
	v_max_i32_e32 v143, v57, v131
	v_cvt_f32_u32_e32 v135, v142
	v_cvt_f32_u32_e32 v134, v143
	v_cmp_gt_u32_e32 vcc, s13, v144
	v_add_u32_e32 v131, v111, v168
	v_pk_fma_f32 v[74:75], v[98:99], v[134:135], v[74:75] neg_lo:[1,0,0] neg_hi:[1,0,0]
	v_cndmask_b32_e32 v57, v180, v130, vcc
	v_add_u32_e32 v130, v110, v168
	v_sub_u32_e32 v134, 0, v131
	v_max_i32_e32 v134, v131, v134
	v_sub_u32_e32 v131, 0, v130
	v_max_i32_e32 v144, v130, v131
	v_cvt_f32_u32_e32 v131, v134
	v_cvt_f32_u32_e32 v130, v144
	v_cmp_gt_u32_e32 vcc, s13, v142
	v_pk_fma_f32 v[130:131], v[98:99], v[130:131], v[58:59] neg_lo:[1,0,0] neg_hi:[1,0,0]
	s_nop 0
	v_cndmask_b32_e32 v170, v180, v75, vcc
	v_cmp_gt_u32_e32 vcc, s13, v143
	v_add_u32_e32 v59, v168, v128
	s_nop 0
	v_cndmask_b32_e32 v75, v180, v74, vcc
	v_cmp_gt_u32_e32 vcc, s13, v134
	v_add_u32_e32 v74, v168, v129
	s_nop 0
	v_cndmask_b32_e32 v58, v180, v131, vcc
	v_sub_u32_e32 v131, 0, v74
	v_max_i32_e32 v74, v74, v131
	v_sub_u32_e32 v131, 0, v59
	v_max_i32_e32 v142, v59, v131
	v_cvt_f32_u32_e32 v135, v74
	v_cvt_f32_u32_e32 v134, v142
	v_cmp_gt_u32_e32 vcc, s13, v144
	v_add_u32_e32 v131, v113, v168
	v_pk_fma_f32 v[76:77], v[98:99], v[134:135], v[76:77] neg_lo:[1,0,0] neg_hi:[1,0,0]
	v_cndmask_b32_e32 v59, v180, v130, vcc
	v_add_u32_e32 v130, v112, v168
	v_sub_u32_e32 v134, 0, v131
	v_max_i32_e32 v134, v131, v134
	v_sub_u32_e32 v131, 0, v130
	v_max_i32_e32 v135, v130, v131
	v_cvt_f32_u32_e32 v131, v134
	v_cvt_f32_u32_e32 v130, v135
	v_cmp_gt_u32_e32 vcc, s13, v74
	v_add_u32_e32 v74, v168, v137
	s_nop 0
	v_cndmask_b32_e32 v172, v180, v77, vcc
	v_cmp_gt_u32_e32 vcc, s13, v142
	v_add_u32_e32 v142, v115, v168
	s_nop 0
	v_cndmask_b32_e32 v173, v180, v76, vcc
	v_pk_fma_f32 v[76:77], v[98:99], v[130:131], v[60:61] neg_lo:[1,0,0] neg_hi:[1,0,0]
	v_cmp_gt_u32_e32 vcc, s13, v134
	v_add_u32_e32 v61, v168, v136
	s_nop 0
	v_cndmask_b32_e32 v60, v180, v77, vcc
	v_sub_u32_e32 v77, 0, v74
	v_max_i32_e32 v74, v74, v77
	v_sub_u32_e32 v77, 0, v61
	v_max_i32_e32 v134, v61, v77
	v_cvt_f32_u32_e32 v131, v74
	v_cvt_f32_u32_e32 v130, v134
	v_cmp_gt_u32_e32 vcc, s13, v135
	v_add_u32_e32 v135, v114, v168
	s_nop 0
	v_cndmask_b32_e32 v61, v180, v76, vcc
	v_pk_fma_f32 v[76:77], v[98:99], v[130:131], v[78:79] neg_lo:[1,0,0] neg_hi:[1,0,0]
	v_sub_u32_e32 v78, 0, v142
	v_max_i32_e32 v130, v142, v78
	v_sub_u32_e32 v78, 0, v135
	v_max_i32_e32 v131, v135, v78
	v_cvt_f32_u32_e32 v79, v130
	v_cvt_f32_u32_e32 v78, v131
	v_cmp_gt_u32_e32 vcc, s13, v74
	v_max_f32_e32 v74, v49, v48
	v_max3_f32 v74, v74, v65, v67
	v_cndmask_b32_e32 v181, v180, v77, vcc
	v_cmp_gt_u32_e32 vcc, s13, v134
	v_max3_f32 v74, v74, v66, v53
	v_max3_f32 v74, v74, v52, v69
	v_cndmask_b32_e32 v182, v180, v76, vcc
	v_pk_fma_f32 v[76:77], v[98:99], v[78:79], v[62:63] neg_lo:[1,0,0] neg_hi:[1,0,0]
	v_cmp_gt_u32_e32 vcc, s13, v130
	v_max3_f32 v74, v74, v68, v57
	v_max3_f32 v74, v74, v56, v73
	v_cndmask_b32_e32 v62, v180, v77, vcc
	v_cmp_gt_u32_e32 vcc, s13, v131
	v_max3_f32 v74, v74, v72, v61
	v_max3_f32 v74, v74, v60, v173
	v_cndmask_b32_e32 v63, v180, v76, vcc
	v_max3_f32 v76, v51, v50, v64
	v_max3_f32 v76, v76, v55, v54
	v_max3_f32 v76, v76, v71, v70
	v_max3_f32 v76, v76, v59, v58
	v_max3_f32 v76, v76, v75, v170
	v_max3_f32 v76, v76, v63, v62
	v_max3_f32 v76, v76, v182, v181
	v_max3_f32 v74, v74, v172, v76
	v_mov_b32_e32 v76, v74
	s_nop 1
	v_permlane32_swap_b32_e32 v74, v76
	v_max_f32_e32 v74, v74, v76
	v_cmp_lt_f32_e32 vcc, s19, v74
	s_cbranch_vccz .LBB0_1333
	v_max_f32_e32 v32, v74, v74
	v_max_f32_e32 v32, 0, v32
	v_exp_f32_e64 v33, -v32
	s_and_saveexec_b64 s[46:47], s[42:43]
	ds_write_b32 v163, v33 offset:49152
	s_or_b64 exec, exec, s[46:47]
	v_add_u32_e32 v46, s25, v80
	ds_read_b128 v[34:37], v46 offset:49216
	ds_read_b128 v[38:41], v46 offset:49248
	ds_read_b128 v[42:45], v46 offset:49152
	ds_read_b128 v[76:79], v46 offset:49184
	v_add_f32_e32 v165, v165, v32
	v_xor_b32_e32 v47, 0x80000000, v165
	v_sub_f32_e32 v49, v49, v32
	v_sub_f32_e32 v48, v48, v32
	v_sub_f32_e32 v51, v51, v32
	v_sub_f32_e32 v50, v50, v32
	v_sub_f32_e32 v53, v53, v32
	v_sub_f32_e32 v52, v52, v32
	v_sub_f32_e32 v55, v55, v32
	v_sub_f32_e32 v54, v54, v32
	v_sub_f32_e32 v57, v57, v32
	v_sub_f32_e32 v56, v56, v32
	v_sub_f32_e32 v59, v59, v32
	v_sub_f32_e32 v58, v58, v32
	v_sub_f32_e32 v61, v61, v32
	v_sub_f32_e32 v60, v60, v32
	v_sub_f32_e32 v63, v63, v32
	v_sub_f32_e32 v62, v62, v32
	v_sub_f32_e32 v65, v65, v32
	v_sub_f32_e32 v64, v64, v32
	v_sub_f32_e32 v67, v67, v32
	v_sub_f32_e32 v66, v66, v32
	v_sub_f32_e32 v69, v69, v32
	v_sub_f32_e32 v68, v68, v32
	v_sub_f32_e32 v71, v71, v32
	v_sub_f32_e32 v70, v70, v32
	v_sub_f32_e32 v73, v73, v32
	v_sub_f32_e32 v72, v72, v32
	v_sub_f32_e32 v75, v75, v32
	v_sub_f32_e32 v170, v170, v32
	v_sub_f32_e32 v173, v173, v32
	v_sub_f32_e32 v172, v172, v32
	v_sub_f32_e32 v182, v182, v32
	v_sub_f32_e32 v181, v181, v32
	v_mul_f32_e32 v162, v162, v33
	s_waitcnt lgkmcnt(2)
	v_pk_mul_f32 v[14:15], v[14:15], v[40:41]
	v_pk_mul_f32 v[12:13], v[12:13], v[38:39]
	v_pk_mul_f32 v[10:11], v[10:11], v[36:37]
	v_pk_mul_f32 v[8:9], v[8:9], v[34:35]
	s_waitcnt lgkmcnt(0)
	v_pk_mul_f32 v[6:7], v[6:7], v[78:79]
	v_pk_mul_f32 v[4:5], v[4:5], v[76:77]
	v_pk_mul_f32 v[2:3], v[2:3], v[44:45]
	v_pk_mul_f32 v[0:1], v[0:1], v[42:43]
	v_pk_mul_f32 v[30:31], v[30:31], v[40:41]
	v_pk_mul_f32 v[28:29], v[28:29], v[38:39]
	v_pk_mul_f32 v[26:27], v[26:27], v[36:37]
	v_pk_mul_f32 v[24:25], v[24:25], v[34:35]
	v_pk_mul_f32 v[22:23], v[22:23], v[78:79]
	v_pk_mul_f32 v[20:21], v[20:21], v[76:77]
	v_pk_mul_f32 v[18:19], v[18:19], v[44:45]
	v_pk_mul_f32 v[16:17], v[16:17], v[42:43]
	v_mov_b32_e32 v46, v47
	v_mov_b32_e32 v45, v47
	v_mov_b32_e32 v44, v47
	v_mov_b32_e32 v43, v47
	v_mov_b32_e32 v42, v47
	v_mov_b32_e32 v41, v47
	v_mov_b32_e32 v40, v47
	v_mov_b32_e32 v39, v47
	v_mov_b32_e32 v38, v47
	v_mov_b32_e32 v37, v47
	v_mov_b32_e32 v36, v47
	v_mov_b32_e32 v35, v47
	v_mov_b32_e32 v34, v47
	v_mov_b32_e32 v33, v47
	v_mov_b32_e32 v32, v47

; template <int MODE> __device__ __forceinline__ void attn_unit(const Unit& a, char* shm) {
;     ...
;             const lds_cptr kp = shm3 + LDS_K + s * KSLOT + hi * 1024 + r32 * 16;
;             f32x16 p0 = negm, p1 = negm;
; #pragma unroll
;             for (int d0 = 0; d0 < ND; ++d0) {
;                 const bf16x8 b0 = *(const LAS bf16x8*)(kp + d0 * 2048), b1 = *(const LAS bf16x8*)(kp + d0 * 2048 + 512);
;                 p0 = __builtin_amdgcn_mfma_f32_32x32x16_bf16(b0, qr[d0], p0, 0, 0, 0);
;                 p1 = __builtin_amdgcn_mfma_f32_32x32x16_bf16(b1, qr[d0], p1, 0, 0, 0);
;             }
;             if (MODE == 1) {
; #pragma unroll
;                 for (int r = 0; r < 16; ++r) { const int ks = 64 * t + crow(r, hi); const int r0 = abs(tq - ks), r1 = abs(tq - ks - 32);
;                     p0[r] = (r0 <= 128) ? p0[r] - a.slope2 * (float)r0 : -INFINITY; p1[r] = (r1 <= 128) ? p1[r] - a.slope2 * (float)r1 : -INFINITY; }
;             }
;     ...
;             float ra = MX3(p0[0], p0[1], p1[0]), rb = MX3(p0[2], p0[3], p1[1]); ra = MX3(ra, p1[2], p1[3]);
; #pragma unroll
;             for (int r = 4; r < 16; r += 4) { ra = MX3(ra, p0[r], p0[r + 1]); rb = MX3(rb, p0[r + 2], p0[r + 3]); ra = MX3(ra, p1[r], p1[r + 1]); rb = MX3(rb, p1[r + 2], p1[r + 3]); }
;     ...
;             float rm = halfmax(__builtin_fmaxf(ra, rb));
;             const bool first = (MODE == 0) && (t == a.t_lo);
;             if (first || __any(rm > THR)) {
;                 const float dl = first ? rm : fmaxf(rm, 0.f);
;                 mhat += dl;
; #pragma unroll
;                 for (int r = 0; r < 16; ++r) { p0[r] -= dl; p1[r] -= dl; negm[r] = -mhat; }
;                 if (!first) {
;                     const float f = __builtin_amdgcn_exp2f(-dl); l_reg *= f;
;                     if (hi == 0) wsf[r32] = f;
; #pragma unroll
;                     for (int r = 0; r < 16; ++r) { const float fr_ = wsf[crow(r, hi)]; o[0][r] *= fr_; o[1][r] *= fr_; }
;                 }
;             }
; #pragma unroll
;             for (int r = 0; r < 16; ++r) { p0[r] = __builtin_amdgcn_exp2f(p0[r]); p1[r] = __builtin_amdgcn_exp2f(p1[r]); }
;             f32x2 s2a = (f32x2){p0[0], p0[1]}, s2b = (f32x2){p1[0], p1[1]};
; #pragma unroll
;             for (int k2 = 1; k2 < 8; ++k2) { s2a += (f32x2){p0[2 * k2], p0[2 * k2 + 1]}; s2b += (f32x2){p1[2 * k2], p1[2 * k2 + 1]}; }
;             s2a += s2b;
.LBB0_1907:
	s_mov_b32 m0, s2
	s_cmpk_gt_u32 s34, 0xff
	s_cselect_b64 s[2:3], -1, 0
	s_cmpk_lt_u32 s34, 0x100
	s_cselect_b64 s[44:45], -1, 0
	v_lshlrev_b32_e32 v0, 10, v145
	v_lshlrev_b32_e32 v1, 4, v144
	v_add3_u32 v146, 0, v0, v1
	ds_read_b128 v[40:43], v146
	ds_read_b128 v[44:47], v146 offset:512
	s_mov_b32 s61, s60
	s_mov_b32 s62, s60
	s_mov_b32 s63, s60
	s_mov_b32 s64, s60
	s_mov_b32 s65, s60
	s_mov_b32 s66, s60
	s_mov_b32 s67, s60
	s_mov_b32 s68, s60
	s_mov_b32 s69, s60
	s_mov_b32 s70, s60
	s_mov_b32 s71, s60
	s_mov_b32 s72, s60
	s_mov_b32 s73, s60
	s_mov_b32 s74, s60
	s_mov_b32 s75, s60
	v_mov_b64_e32 v[0:1], s[60:61]
	v_mov_b64_e32 v[2:3], s[62:63]
	v_mov_b64_e32 v[4:5], s[64:65]
	v_mov_b64_e32 v[6:7], s[66:67]
	v_mov_b64_e32 v[8:9], s[68:69]
	v_mov_b64_e32 v[10:11], s[70:71]
	v_mov_b64_e32 v[12:13], s[72:73]
	v_mov_b64_e32 v[14:15], s[74:75]
	v_lshlrev_b32_e32 v48, 1, v32
	v_and_b32_e32 v48, 32, v48
	s_waitcnt lgkmcnt(0)
	v_mfma_f32_32x32x16_bf16 v[16:31], v[40:43], v[82:85], v[0:15]
	v_lshlrev_b32_e32 v32, 4, v32
	v_add3_u32 v33, 0, v48, v33
	v_and_b32_e32 v32, 0xc0, v32
	s_and_b64 vcc, exec, s[2:3]
	v_mfma_f32_32x32x16_bf16 v[0:15], v[44:47], v[82:85], v[0:15]
	ds_read_b128 v[40:43], v146 offset:2048
	ds_read_b128 v[44:47], v146 offset:2560
	s_waitcnt lgkmcnt(1)
	v_mfma_f32_32x32x16_bf16 v[16:31], v[40:43], v[86:89], v[16:31]
	s_waitcnt lgkmcnt(0)
	v_mfma_f32_32x32x16_bf16 v[0:15], v[44:47], v[86:89], v[0:15]
	ds_read_b128 v[40:43], v146 offset:4096
	ds_read_b128 v[44:47], v146 offset:4608
	s_waitcnt lgkmcnt(1)
	v_mfma_f32_32x32x16_bf16 v[16:31], v[40:43], v[90:93], v[16:31]
	s_waitcnt lgkmcnt(0)
	v_mfma_f32_32x32x16_bf16 v[0:15], v[44:47], v[90:93], v[0:15]
	ds_read_b128 v[40:43], v146 offset:6144
	ds_read_b128 v[44:47], v146 offset:6656
	s_waitcnt lgkmcnt(1)
	v_mfma_f32_32x32x16_bf16 v[16:31], v[40:43], v[94:97], v[16:31]
	s_waitcnt lgkmcnt(0)
	v_mfma_f32_32x32x16_bf16 v[0:15], v[44:47], v[94:97], v[0:15]
	ds_read_b128 v[40:43], v146 offset:8192
	ds_read_b128 v[44:47], v146 offset:8704
	s_waitcnt lgkmcnt(1)
	v_mfma_f32_32x32x16_bf16 v[16:31], v[40:43], v[98:101], v[16:31]
	s_waitcnt lgkmcnt(0)
	v_mfma_f32_32x32x16_bf16 v[0:15], v[44:47], v[98:101], v[0:15]
	ds_read_b128 v[40:43], v146 offset:10240
	ds_read_b128 v[44:47], v146 offset:10752
	s_waitcnt lgkmcnt(1)
	v_mfma_f32_32x32x16_bf16 v[16:31], v[40:43], v[102:105], v[16:31]
	v_lshlrev_b32_e32 v40, 8, v145
	v_add3_u32 v147, v33, v40, v32
	s_waitcnt lgkmcnt(0)
	v_mfma_f32_32x32x16_bf16 v[0:15], v[44:47], v[102:105], v[0:15]
	s_nop 7
	v_max_f32_e32 v32, v17, v17
	v_max_f32_e32 v33, v16, v16
	v_max_f32_e32 v32, v33, v32
	s_nop 0
	v_max3_f32 v33, v18, v19, v1
	v_max3_f32 v32, v32, v0, v2
	v_max3_f32 v32, v32, v3, v20
	v_max3_f32 v33, v33, v22, v23
	v_max3_f32 v32, v32, v21, v4
	v_max3_f32 v33, v33, v6, v7
	v_max3_f32 v32, v32, v5, v24
	v_max3_f32 v33, v33, v26, v27
	v_max3_f32 v32, v32, v25, v8
	v_max3_f32 v33, v33, v10, v11
	v_max3_f32 v32, v32, v9, v28
	v_max3_f32 v33, v33, v30, v31
	v_max3_f32 v32, v32, v29, v12
	v_max3_f32 v33, v33, v14, v15
	v_max3_f32 v32, v32, v13, v33
	v_mov_b32_e32 v33, v32
	s_nop 1
	v_permlane32_swap_b32_e32 v32, v33
	v_max_f32_e32 v32, v32, v33
	v_sub_f32_e32 v16, v16, v32
	v_sub_f32_e32 v0, v0, v32
	v_sub_f32_e32 v17, v17, v32
	v_sub_f32_e32 v1, v1, v32
	v_sub_f32_e32 v18, v18, v32
	v_sub_f32_e32 v2, v2, v32
	v_sub_f32_e32 v19, v19, v32
	v_sub_f32_e32 v3, v3, v32
	v_sub_f32_e32 v20, v20, v32
	v_sub_f32_e32 v4, v4, v32
	v_sub_f32_e32 v21, v21, v32
	v_sub_f32_e32 v5, v5, v32
	v_sub_f32_e32 v22, v22, v32
	v_sub_f32_e32 v6, v6, v32
	v_sub_f32_e32 v23, v23, v32
	v_sub_f32_e32 v7, v7, v32
	v_sub_f32_e32 v24, v24, v32
	v_sub_f32_e32 v8, v8, v32
	v_sub_f32_e32 v25, v25, v32
	v_sub_f32_e32 v9, v9, v32
	v_sub_f32_e32 v26, v26, v32
	v_sub_f32_e32 v10, v10, v32
	v_sub_f32_e32 v27, v27, v32
	v_sub_f32_e32 v11, v11, v32
	v_sub_f32_e32 v28, v28, v32
	v_sub_f32_e32 v12, v12, v32
	v_sub_f32_e32 v29, v29, v32
	v_sub_f32_e32 v13, v13, v32
	v_sub_f32_e32 v30, v30, v32
	v_sub_f32_e32 v14, v14, v32
	v_sub_f32_e32 v31, v31, v32
	v_sub_f32_e32 v15, v15, v32
	v_exp_f32_e32 v106, v16
	v_exp_f32_e32 v74, v0
	v_exp_f32_e32 v107, v17
	v_exp_f32_e32 v75, v1
	v_exp_f32_e32 v112, v18
	v_exp_f32_e32 v110, v2
	v_exp_f32_e32 v113, v19
	v_exp_f32_e32 v111, v3
	v_exp_f32_e32 v108, v20
	v_exp_f32_e32 v78, v4
	v_exp_f32_e32 v109, v21
	v_exp_f32_e32 v79, v5
	v_exp_f32_e32 v76, v22
	v_exp_f32_e32 v72, v6
	v_exp_f32_e32 v77, v23
	v_exp_f32_e32 v73, v7
	v_exp_f32_e32 v70, v24
	v_exp_f32_e32 v68, v8
	v_exp_f32_e32 v71, v25
	v_exp_f32_e32 v69, v9
	v_exp_f32_e32 v66, v26
	v_exp_f32_e32 v64, v10
	v_exp_f32_e32 v67, v27
	v_exp_f32_e32 v65, v11
	v_exp_f32_e32 v46, v28
	v_exp_f32_e32 v44, v12
	v_exp_f32_e32 v47, v29
	v_exp_f32_e32 v45, v13
	v_exp_f32_e32 v42, v30
	v_exp_f32_e32 v40, v14
	v_exp_f32_e32 v43, v31
	v_exp_f32_e32 v41, v15
	v_mov_b32_e32 v0, 0
	v_mov_b32_e32 v1, 0
	v_mov_b32_e32 v2, 0
	v_mov_b32_e32 v3, 0
	v_mov_b32_e32 v4, 0
	v_mov_b32_e32 v5, 0
	v_mov_b32_e32 v6, 0
	v_mov_b32_e32 v7, 0
	v_mov_b32_e32 v8, 0
	v_mov_b32_e32 v9, 0
	v_mov_b32_e32 v10, 0
	v_mov_b32_e32 v11, 0
	v_mov_b32_e32 v12, 0
	v_mov_b32_e32 v13, 0
	v_mov_b32_e32 v14, 0
	v_mov_b32_e32 v15, 0
	v_mov_b32_e32 v16, 0
	v_mov_b32_e32 v17, 0
	v_mov_b32_e32 v18, 0
	v_mov_b32_e32 v19, 0
	v_mov_b32_e32 v20, 0
	v_mov_b32_e32 v21, 0
	v_mov_b32_e32 v22, 0
	v_mov_b32_e32 v23, 0
	v_mov_b32_e32 v24, 0
	v_mov_b32_e32 v25, 0
	v_mov_b32_e32 v26, 0
	v_mov_b32_e32 v27, 0
	v_mov_b32_e32 v28, 0
	v_mov_b32_e32 v29, 0
	v_mov_b32_e32 v30, 0
	v_mov_b32_e32 v31, 0
	v_cvt_pk_bf16_f32 v60, v106, v107
	v_cvt_pk_bf16_f32 v56, v70, v71
	v_cvt_pk_bf16_f32 v52, v74, v75
	v_cvt_pk_bf16_f32 v48, v68, v69
	v_cvt_pk_bf16_f32 v61, v112, v113
	v_cvt_pk_bf16_f32 v57, v66, v67
	v_cvt_pk_bf16_f32 v53, v110, v111
	v_cvt_pk_bf16_f32 v49, v64, v65
	v_cvt_pk_bf16_f32 v62, v108, v109
	v_cvt_pk_bf16_f32 v58, v46, v47
	v_cvt_pk_bf16_f32 v54, v78, v79
	v_cvt_pk_bf16_f32 v50, v44, v45
	v_cvt_pk_bf16_f32 v63, v76, v77
	v_cvt_pk_bf16_f32 v59, v42, v43
	v_cvt_pk_bf16_f32 v55, v72, v73
	v_cvt_pk_bf16_f32 v51, v40, v41
	s_cbranch_vccz .Lmla_apv0
	ds_read_b64_tr_b16 v[230:231], v147 offset:24576
	ds_read_b64_tr_b16 v[232:233], v147 offset:25088
	ds_read_b64_tr_b16 v[234:235], v147 offset:25600
	ds_read_b64_tr_b16 v[236:237], v147 offset:26112
	ds_read_b64_tr_b16 v[238:239], v147 offset:26624
	ds_read_b64_tr_b16 v[240:241], v147 offset:27136
	ds_read_b64_tr_b16 v[242:243], v147 offset:27648
	ds_read_b64_tr_b16 v[244:245], v147 offset:28160
	ds_read_b64_tr_b16 v[246:247], v147 offset:28672
	ds_read_b64_tr_b16 v[248:249], v147 offset:29184
	ds_read_b64_tr_b16 v[150:151], v147 offset:29696
	ds_read_b64_tr_b16 v[152:153], v147 offset:30208
	ds_read_b64_tr_b16 v[154:155], v147 offset:30720
	ds_read_b64_tr_b16 v[156:157], v147 offset:31232
	ds_read_b64_tr_b16 v[158:159], v147 offset:31744
	ds_read_b64_tr_b16 v[160:161], v147 offset:32256
	s_branch .LBB0_1909

; #define LAS __attribute__((address_space(3)))
; __device__ __forceinline__ int crow(int r, int hi) { return (r & 3) + 8 * (r >> 2) + 4 * hi; }
; __device__ __forceinline__ float halfmax(float m) { auto rr = __builtin_amdgcn_permlane32_swap(__float_as_uint(m), __float_as_uint(m), false, false); return fmaxf(__uint_as_float(rr[0]), __uint_as_float(rr[1])); }
; #define MX3(a_, b_, c_) __builtin_fmaxf(__builtin_fmaxf((a_), (b_)), (c_))
; template <int MODE> __device__ __forceinline__ void attn_unit(const Unit& a, char* shm) {
;     ...
;             for (int d0 = 0; d0 < ND; ++d0) {
;                 const bf16x8 b0 = *(const LAS bf16x8*)(kp + d0 * 2048), b1 = *(const LAS bf16x8*)(kp + d0 * 2048 + 512);
;                 p0 = __builtin_amdgcn_mfma_f32_32x32x16_bf16(b0, qr[d0], p0, 0, 0, 0);
;                 p1 = __builtin_amdgcn_mfma_f32_32x32x16_bf16(b1, qr[d0], p1, 0, 0, 0);
;             }
;             if (MODE == 1) {
; #pragma unroll
;                 for (int r = 0; r < 16; ++r) { const int ks = 64 * t + crow(r, hi); const int r0 = abs(tq - ks), r1 = abs(tq - ks - 32);
;                     p0[r] = (r0 <= 128) ? p0[r] - a.slope2 * (float)r0 : -INFINITY; p1[r] = (r1 <= 128) ? p1[r] - a.slope2 * (float)r1 : -INFINITY; }
;             }
;     ...
;             float ra = MX3(p0[0], p0[1], p1[0]), rb = MX3(p0[2], p0[3], p1[1]); ra = MX3(ra, p1[2], p1[3]);
; #pragma unroll
;             for (int r = 4; r < 16; r += 4) { ra = MX3(ra, p0[r], p0[r + 1]); rb = MX3(rb, p0[r + 2], p0[r + 3]); ra = MX3(ra, p1[r], p1[r + 1]); rb = MX3(rb, p1[r + 2], p1[r + 3]); }
;     ...
;             float rm = halfmax(__builtin_fmaxf(ra, rb));
;             const bool first = (MODE == 0) && (t == a.t_lo);
;             if (first || __any(rm > THR)) {
;                 const float dl = first ? rm : fmaxf(rm, 0.f);
;                 mhat += dl;
; #pragma unroll
;                 for (int r = 0; r < 16; ++r) { p0[r] -= dl; p1[r] -= dl; negm[r] = -mhat; }
;                 if (!first) {
;                     const float f = __builtin_amdgcn_exp2f(-dl); l_reg *= f;
;                     if (hi == 0) wsf[r32] = f;
; #pragma unroll
;                     for (int r = 0; r < 16; ++r) { const float fr_ = wsf[crow(r, hi)]; o[0][r] *= fr_; o[1][r] *= fr_; }
.Lmla_nokpe:
	s_waitcnt lgkmcnt(9)
	v_mfma_f32_32x32x16_bf16 v[48:63], v[190:193], v[86:89], v[48:63]
	s_lshl_b32 s0, s35, 13
	s_add_i32 s1, s0, s48
	s_mov_b32 m0, s1
	s_nop 0
	global_load_lds_dwordx4 v[106:107], off
	s_mov_b32 m0, s12
	s_waitcnt lgkmcnt(8)
	v_mfma_f32_32x32x16_bf16 v[64:79], v[194:197], v[86:89], v[64:79]
	s_waitcnt lgkmcnt(7)
	v_mfma_f32_32x32x16_bf16 v[48:63], v[198:201], v[90:93], v[48:63]
	s_waitcnt lgkmcnt(6)
	v_mfma_f32_32x32x16_bf16 v[64:79], v[202:205], v[90:93], v[64:79]
	s_waitcnt lgkmcnt(5)
	v_mfma_f32_32x32x16_bf16 v[48:63], v[206:209], v[94:97], v[48:63]
	s_waitcnt lgkmcnt(4)
	v_mfma_f32_32x32x16_bf16 v[64:79], v[210:213], v[94:97], v[64:79]
	s_waitcnt lgkmcnt(3)
	v_mfma_f32_32x32x16_bf16 v[48:63], v[214:217], v[98:101], v[48:63]
	s_waitcnt lgkmcnt(2)
	v_mfma_f32_32x32x16_bf16 v[64:79], v[218:221], v[98:101], v[64:79]
	s_waitcnt lgkmcnt(1)
	v_mfma_f32_32x32x16_bf16 v[48:63], v[222:225], v[102:105], v[48:63]
	s_waitcnt lgkmcnt(0)
	v_mfma_f32_32x32x16_bf16 v[64:79], v[226:229], v[102:105], v[64:79]
	ds_read_b64_tr_b16 v[230:231], v149 offset:24576
	ds_read_b64_tr_b16 v[232:233], v149 offset:25088
	ds_read_b64_tr_b16 v[234:235], v149 offset:25600
	ds_read_b64_tr_b16 v[236:237], v149 offset:26112
	ds_read_b64_tr_b16 v[238:239], v149 offset:26624
	ds_read_b64_tr_b16 v[240:241], v149 offset:27136
	ds_read_b64_tr_b16 v[242:243], v149 offset:27648
	ds_read_b64_tr_b16 v[244:245], v149 offset:28160
	ds_read_b64_tr_b16 v[246:247], v149 offset:28672
	ds_read_b64_tr_b16 v[248:249], v149 offset:29184
	ds_read_b64_tr_b16 v[150:151], v149 offset:29696
	ds_read_b64_tr_b16 v[152:153], v149 offset:30208
	ds_read_b64_tr_b16 v[154:155], v149 offset:30720
	ds_read_b64_tr_b16 v[156:157], v149 offset:31232
	v_max_f32_e32 v118, v48, v49
	v_max3_f32 v114, v50, v51, v65
	v_max3_f32 v115, v118, v64, v66
	v_max3_f32 v115, v115, v67, v52
	v_max3_f32 v114, v114, v54, v55
	v_max3_f32 v115, v115, v53, v68
	v_max3_f32 v114, v114, v70, v71
	v_max3_f32 v115, v115, v69, v56
	v_max3_f32 v114, v114, v58, v59
	v_max3_f32 v115, v115, v57, v72
	v_max3_f32 v114, v114, v74, v75
	v_max3_f32 v115, v115, v73, v60
	v_max3_f32 v114, v114, v62, v63
	v_max3_f32 v115, v115, v61, v76
	v_max3_f32 v114, v114, v78, v79
	v_max3_f32 v114, v115, v77, v114
	v_mov_b32_e32 v115, v114
	s_nop 1
	v_permlane32_swap_b32_e32 v114, v115
	v_max_f32_e32 v114, v114, v115
	v_cmp_lt_f32_e32 vcc, s19, v114
	s_cbranch_vccz .LBB0_1920
	s_waitcnt lgkmcnt(0)
	v_max_f32_e32 v32, v114, v114
	v_max_f32_e32 v32, 0, v32
	v_exp_f32_e64 v33, -v32
	s_and_saveexec_b64 s[46:47], s[42:43]
	ds_write_b32 v148, v33 offset:49152
	s_or_b64 exec, exec, s[46:47]
	v_pk_add_f32 v[114:115], v[112:113], v[32:33]
	v_pk_mul_f32 v[40:41], v[112:113], v[32:33]
	v_add_u32_e32 v44, s49, v80
	v_pk_add_f32 v[48:49], v[48:49], v[32:33] op_sel_hi:[1,0] neg_lo:[0,1] neg_hi:[0,1]
	v_pk_add_f32 v[64:65], v[64:65], v[32:33] op_sel_hi:[1,0] neg_lo:[0,1] neg_hi:[0,1]
	v_pk_add_f32 v[50:51], v[50:51], v[32:33] op_sel_hi:[1,0] neg_lo:[0,1] neg_hi:[0,1]
	v_pk_add_f32 v[66:67], v[66:67], v[32:33] op_sel_hi:[1,0] neg_lo:[0,1] neg_hi:[0,1]
	v_pk_add_f32 v[52:53], v[52:53], v[32:33] op_sel_hi:[1,0] neg_lo:[0,1] neg_hi:[0,1]
	v_pk_add_f32 v[68:69], v[68:69], v[32:33] op_sel_hi:[1,0] neg_lo:[0,1] neg_hi:[0,1]
	v_pk_add_f32 v[54:55], v[54:55], v[32:33] op_sel_hi:[1,0] neg_lo:[0,1] neg_hi:[0,1]
	v_pk_add_f32 v[70:71], v[70:71], v[32:33] op_sel_hi:[1,0] neg_lo:[0,1] neg_hi:[0,1]
	v_pk_add_f32 v[56:57], v[56:57], v[32:33] op_sel_hi:[1,0] neg_lo:[0,1] neg_hi:[0,1]
	v_pk_add_f32 v[72:73], v[72:73], v[32:33] op_sel_hi:[1,0] neg_lo:[0,1] neg_hi:[0,1]
	v_pk_add_f32 v[58:59], v[58:59], v[32:33] op_sel_hi:[1,0] neg_lo:[0,1] neg_hi:[0,1]
	v_pk_add_f32 v[74:75], v[74:75], v[32:33] op_sel_hi:[1,0] neg_lo:[0,1] neg_hi:[0,1]
	v_pk_add_f32 v[60:61], v[60:61], v[32:33] op_sel_hi:[1,0] neg_lo:[0,1] neg_hi:[0,1]
	v_pk_add_f32 v[76:77], v[76:77], v[32:33] op_sel_hi:[1,0] neg_lo:[0,1] neg_hi:[0,1]
	v_pk_add_f32 v[62:63], v[62:63], v[32:33] op_sel_hi:[1,0] neg_lo:[0,1] neg_hi:[0,1]
	v_pk_add_f32 v[78:79], v[78:79], v[32:33] op_sel_hi:[1,0] neg_lo:[0,1] neg_hi:[0,1]
	ds_read_b128 v[32:35], v44 offset:49216
	ds_read_b128 v[36:39], v44 offset:49248
	v_mov_b32_e32 v115, v41
	ds_read_b128 v[40:43], v44 offset:49152
	ds_read_b128 v[116:119], v44 offset:49184
	v_pk_add_f32 v[46:47], v[114:115], 0 neg_lo:[1,1] neg_hi:[1,1]
	s_waitcnt lgkmcnt(3)
	v_pk_mul_f32 v[26:27], v[26:27], v[34:35]
	s_waitcnt lgkmcnt(2)
	v_pk_mul_f32 v[30:31], v[30:31], v[38:39]
	v_pk_mul_f32 v[28:29], v[28:29], v[36:37]
	v_pk_mul_f32 v[24:25], v[24:25], v[32:33]
	s_waitcnt lgkmcnt(0)
	v_pk_mul_f32 v[22:23], v[22:23], v[118:119]
	v_pk_mul_f32 v[20:21], v[20:21], v[116:117]
	v_pk_mul_f32 v[18:19], v[18:19], v[42:43]
	v_pk_mul_f32 v[16:17], v[16:17], v[40:41]
	v_pk_mul_f32 v[14:15], v[14:15], v[38:39]
	v_pk_mul_f32 v[12:13], v[12:13], v[36:37]
	v_pk_mul_f32 v[10:11], v[10:11], v[34:35]
	v_pk_mul_f32 v[8:9], v[8:9], v[32:33]
	v_pk_mul_f32 v[6:7], v[6:7], v[118:119]
	v_pk_mul_f32 v[4:5], v[4:5], v[116:117]
	v_pk_mul_f32 v[2:3], v[2:3], v[42:43]
	v_pk_mul_f32 v[0:1], v[0:1], v[40:41]
	v_mov_b32_e32 v47, v46
	v_mov_b32_e32 v45, v46
	v_mov_b32_e32 v44, v46
	v_mov_b32_e32 v43, v46
	v_mov_b32_e32 v42, v46
	v_mov_b32_e32 v41, v46
	v_mov_b32_e32 v40, v46
	v_mov_b32_e32 v39, v46
	v_mov_b32_e32 v38, v46
	v_mov_b32_e32 v37, v46
	v_mov_b32_e32 v36, v46
	v_mov_b32_e32 v35, v46
	v_mov_b32_e32 v34, v46
	v_mov_b32_e32 v33, v46
	v_mov_b32_e32 v32, v46
	v_mov_b64_e32 v[112:113], v[114:115]
